# final RMSNorm phase writes the f32 outputs with non-temporal stores (nothing reads them again; fewer dirty L2 lines at kernel end)
# speedup vs baseline: 1.0034x; 1.0034x over previous
; #define LAS __attribute__((address_space(3)))
; __device__ __forceinline__ float bf_lo(unsigned w) { return __uint_as_float(w << 16); }
; __device__ __forceinline__ float bf_hi(unsigned w) { return __uint_as_float(w & 0xffff0000u); }
; __device__ __forceinline__ f32x4 ld_bf4(const bf16_t* p) { const u32x2 w = *(const u32x2*)p; return (f32x4){bf_lo(w.x), bf_hi(w.x), bf_lo(w.y), bf_hi(w.y)}; }
; __device__ __forceinline__ void pf_row_finish(Frame& F, const LAS signed char* rem, int row, const u32x2 (&w)[16], const f32x4 (&gfv)[16]) {
;     const bf16_t* PART = WSP(bf16_t, WS_PART); const bf16_t* X1 = WSP(bf16_t, WS_X1);
;     float* o = F.out + (size_t)row * DM; f32x4 v[16]; float ss = 0.f;
; #pragma unroll
;     for (int j = 0; j < 16; ++j) { const int c = 256 * j + 4 * F.lane; const int tl = rem[(row >> 8) * 16 + j];
;         if (tl < 0) v[j] = (f32x4){bf_lo(w[j].x), bf_hi(w[j].x), bf_lo(w[j].y), bf_hi(w[j].y)};
;         else { f32x4 a = ld_bf4(X1 + (size_t)row * DM + c);
; #pragma unroll
;             for (int ks = 0; ks < 8; ++ks) a += ld_bf4(PART + ((size_t)(tl * 8 + ks) << 16) + (row & 255) * 256 + 4 * F.lane);
;             v[j] = a; }
;         ss += (v[j][0] * v[j][0] + v[j][1] * v[j][1]) + (v[j][2] * v[j][2] + v[j][3] * v[j][3]); }
;     const float rs = rsqrtf(wave_sum(ss) * (1.0f / DM) + EPS);
.LBB0_2955:
	s_waitcnt vmcnt(32)
	v_pk_mul_f32 v[168:169], v[66:67], v[66:67]
	v_pk_mul_f32 v[170:171], v[64:65], v[64:65]
	s_lshl_b64 s[0:1], s[4:5], 12
	v_pk_mov_b32 v[172:173], v[170:171], v[168:169] op_sel:[1,0]
	v_mov_b32_e32 v171, v169
	v_pk_add_f32 v[168:169], v[172:173], v[170:171]
	v_pk_mul_f32 v[170:171], v[70:71], v[70:71]
	v_pk_mul_f32 v[172:173], v[68:69], v[68:69]
	v_pk_add_f32 v[168:169], v[168:169], v[168:169] op_sel:[0,1] op_sel_hi:[1,0]
	v_pk_mov_b32 v[174:175], v[172:173], v[170:171] op_sel:[1,0]
	v_mov_b32_e32 v173, v171
	v_pk_add_f32 v[170:171], v[174:175], v[172:173]
	v_mul_f32_e32 v172, v76, v76
	v_mul_f32_e32 v173, v77, v77
	v_pk_add_f32 v[170:171], v[170:171], v[170:171] op_sel:[0,1] op_sel_hi:[1,0]
	v_mov_b32_e32 v169, v172
	v_mov_b32_e32 v171, v173
	v_pk_add_f32 v[168:169], v[168:169], v[170:171]
	v_mul_f32_e32 v170, v73, v73
	v_mul_f32_e32 v172, v75, v75
	v_mul_f32_e32 v174, v78, v78
	v_mul_f32_e32 v175, v79, v79
	v_pk_fma_f32 v[170:171], v[72:73], v[72:73], v[170:171] op_sel_hi:[1,1,0]
	v_pk_fma_f32 v[172:173], v[74:75], v[74:75], v[172:173] op_sel_hi:[1,1,0]
	v_mov_b32_e32 v171, v174
	v_mov_b32_e32 v173, v175
	v_pk_add_f32 v[170:171], v[170:171], v[172:173]
	v_pk_mul_f32 v[172:173], v[80:81], v[80:81]
	v_pk_add_f32 v[168:169], v[168:169], v[170:171]
	v_pk_mul_f32 v[170:171], v[82:83], v[82:83]
	v_pk_add_f32 v[168:169], v[168:169], v[168:169] op_sel:[0,1] op_sel_hi:[1,0]
	v_pk_mov_b32 v[174:175], v[172:173], v[170:171] op_sel:[1,0]
	v_mov_b32_e32 v173, v171
	v_pk_add_f32 v[170:171], v[174:175], v[172:173]
	v_mul_f32_e32 v172, v88, v88
	v_mul_f32_e32 v173, v89, v89
	v_pk_add_f32 v[170:171], v[170:171], v[170:171] op_sel:[0,1] op_sel_hi:[1,0]
	v_mov_b32_e32 v169, v172
	v_mov_b32_e32 v171, v173
	v_pk_add_f32 v[168:169], v[168:169], v[170:171]
	v_mul_f32_e32 v170, v85, v85
	v_mul_f32_e32 v172, v87, v87
	v_mul_f32_e32 v174, v90, v90
	v_mul_f32_e32 v175, v91, v91
	v_pk_fma_f32 v[170:171], v[84:85], v[84:85], v[170:171] op_sel_hi:[1,1,0]
	v_pk_fma_f32 v[172:173], v[86:87], v[86:87], v[172:173] op_sel_hi:[1,1,0]
	v_mov_b32_e32 v171, v174
	v_mov_b32_e32 v173, v175
	v_pk_add_f32 v[170:171], v[170:171], v[172:173]
	v_pk_mul_f32 v[172:173], v[92:93], v[92:93]
	v_pk_add_f32 v[168:169], v[168:169], v[170:171]
	v_pk_mul_f32 v[170:171], v[94:95], v[94:95]
	v_pk_add_f32 v[168:169], v[168:169], v[168:169] op_sel:[0,1] op_sel_hi:[1,0]
	v_pk_mov_b32 v[174:175], v[172:173], v[170:171] op_sel:[1,0]
	v_mov_b32_e32 v173, v171
	v_pk_add_f32 v[170:171], v[174:175], v[172:173]
	v_mul_f32_e32 v172, v100, v100
	v_mul_f32_e32 v173, v101, v101
	v_pk_add_f32 v[170:171], v[170:171], v[170:171] op_sel:[0,1] op_sel_hi:[1,0]
	v_mov_b32_e32 v169, v172
	v_mov_b32_e32 v171, v173
	v_pk_add_f32 v[168:169], v[168:169], v[170:171]
	v_mul_f32_e32 v170, v97, v97
	v_mul_f32_e32 v172, v99, v99
	v_mul_f32_e32 v174, v102, v102
	v_mul_f32_e32 v175, v103, v103
	v_pk_fma_f32 v[170:171], v[96:97], v[96:97], v[170:171] op_sel_hi:[1,1,0]
	v_pk_fma_f32 v[172:173], v[98:99], v[98:99], v[172:173] op_sel_hi:[1,1,0]
	v_mov_b32_e32 v171, v174
	v_mov_b32_e32 v173, v175
	v_pk_add_f32 v[170:171], v[170:171], v[172:173]
	v_pk_mul_f32 v[172:173], v[104:105], v[104:105]
	v_pk_add_f32 v[168:169], v[168:169], v[170:171]
	v_pk_mul_f32 v[170:171], v[106:107], v[106:107]
	v_pk_add_f32 v[168:169], v[168:169], v[168:169] op_sel:[0,1] op_sel_hi:[1,0]
	v_pk_mov_b32 v[174:175], v[172:173], v[170:171] op_sel:[1,0]
	v_mov_b32_e32 v173, v171
	v_pk_add_f32 v[170:171], v[174:175], v[172:173]
	v_mul_f32_e32 v172, v112, v112
	v_mul_f32_e32 v173, v113, v113
	v_pk_add_f32 v[170:171], v[170:171], v[170:171] op_sel:[0,1] op_sel_hi:[1,0]
	v_mov_b32_e32 v169, v172
	v_mov_b32_e32 v171, v173
	v_pk_add_f32 v[168:169], v[168:169], v[170:171]
	v_mul_f32_e32 v170, v109, v109
	v_mul_f32_e32 v172, v111, v111
	v_mul_f32_e32 v174, v114, v114
	v_mul_f32_e32 v175, v115, v115
	v_pk_fma_f32 v[170:171], v[108:109], v[108:109], v[170:171] op_sel_hi:[1,1,0]
	v_pk_fma_f32 v[172:173], v[110:111], v[110:111], v[172:173] op_sel_hi:[1,1,0]
	v_mov_b32_e32 v171, v174
	v_mov_b32_e32 v173, v175
	v_pk_add_f32 v[170:171], v[170:171], v[172:173]
	v_pk_mul_f32 v[172:173], v[116:117], v[116:117]
	v_pk_add_f32 v[168:169], v[168:169], v[170:171]
	v_pk_mul_f32 v[170:171], v[118:119], v[118:119]
	v_pk_add_f32 v[168:169], v[168:169], v[168:169] op_sel:[0,1] op_sel_hi:[1,0]
	v_pk_mov_b32 v[174:175], v[172:173], v[170:171] op_sel:[1,0]
	v_mov_b32_e32 v173, v171
	v_pk_add_f32 v[170:171], v[174:175], v[172:173]
	v_mul_f32_e32 v172, v124, v124
	v_mul_f32_e32 v173, v125, v125
	v_pk_add_f32 v[170:171], v[170:171], v[170:171] op_sel:[0,1] op_sel_hi:[1,0]
	v_mov_b32_e32 v169, v172
	v_mov_b32_e32 v171, v173
	v_pk_add_f32 v[168:169], v[168:169], v[170:171]
	v_mul_f32_e32 v170, v121, v121
	v_mul_f32_e32 v172, v123, v123
	v_mul_f32_e32 v174, v126, v126
	v_mul_f32_e32 v175, v127, v127
	v_pk_fma_f32 v[170:171], v[120:121], v[120:121], v[170:171] op_sel_hi:[1,1,0]
	v_pk_fma_f32 v[172:173], v[122:123], v[122:123], v[172:173] op_sel_hi:[1,1,0]
	v_mov_b32_e32 v171, v174
	v_mov_b32_e32 v173, v175
	v_pk_add_f32 v[170:171], v[170:171], v[172:173]
	s_lshl_b64 s[0:1], s[0:1], 2
	v_pk_add_f32 v[168:169], v[168:169], v[170:171]
	s_add_u32 s0, s84, s0
	v_add_f32_e32 v168, v168, v169
	ds_bpermute_b32 v169, v206, v168
	s_addc_u32 s1, s85, s1
	v_lshl_add_u64 v[170:171], s[0:1], 0, v[128:129]
	s_waitcnt lgkmcnt(0)
; #define LAS __attribute__((address_space(3)))
; __device__ __forceinline__ float bf_lo(unsigned w) { return __uint_as_float(w << 16); }
; __device__ __forceinline__ float bf_hi(unsigned w) { return __uint_as_float(w & 0xffff0000u); }
; __device__ __forceinline__ f32x4 ld_bf4(const bf16_t* p) { const u32x2 w = *(const u32x2*)p; return (f32x4){bf_lo(w.x), bf_hi(w.x), bf_lo(w.y), bf_hi(w.y)}; }
; __device__ __forceinline__ void pf_row_finish(Frame& F, const LAS signed char* rem, int row, const u32x2 (&w)[16], const f32x4 (&gfv)[16]) {
;     const bf16_t* PART = WSP(bf16_t, WS_PART); const bf16_t* X1 = WSP(bf16_t, WS_X1);
;     float* o = F.out + (size_t)row * DM; f32x4 v[16]; float ss = 0.f;
; #pragma unroll
;     for (int j = 0; j < 16; ++j) { const int c = 256 * j + 4 * F.lane; const int tl = rem[(row >> 8) * 16 + j];
;         if (tl < 0) v[j] = (f32x4){bf_lo(w[j].x), bf_hi(w[j].x), bf_lo(w[j].y), bf_hi(w[j].y)};
;         else { f32x4 a = ld_bf4(X1 + (size_t)row * DM + c);
; #pragma unroll
;             for (int ks = 0; ks < 8; ++ks) a += ld_bf4(PART + ((size_t)(tl * 8 + ks) << 16) + (row & 255) * 256 + 4 * F.lane);
;             v[j] = a; }
;         ss += (v[j][0] * v[j][0] + v[j][1] * v[j][1]) + (v[j][2] * v[j][2] + v[j][3] * v[j][3]); }
;     const float rs = rsqrtf(wave_sum(ss) * (1.0f / DM) + EPS);
; #pragma unroll
;     for (int j = 0; j < 16; ++j) *(f32x4*)(o + 256 * j + 4 * F.lane) = v[j] * rs * gfv[j];
; }
	v_add_f32_e32 v168, v168, v169
	ds_bpermute_b32 v169, v207, v168
	s_waitcnt lgkmcnt(0)
	v_add_f32_e32 v168, v168, v169
	ds_bpermute_b32 v169, v208, v168
	s_waitcnt lgkmcnt(0)
	v_add_f32_e32 v168, v168, v169
	ds_bpermute_b32 v169, v209, v168
	s_waitcnt lgkmcnt(0)
	v_add_f32_e32 v168, v168, v169
	ds_bpermute_b32 v169, v210, v168
	s_waitcnt lgkmcnt(0)
	v_add_f32_e32 v168, v168, v169
	ds_bpermute_b32 v169, v211, v168
	s_waitcnt lgkmcnt(0)
	v_add_f32_e32 v168, v168, v169
	v_fmamk_f32 v168, v168, 0x39800000, v145
	v_mul_f32_e32 v169, 0x4b800000, v168
	v_cmp_gt_f32_e32 vcc, s30, v168
	s_nop 1
	v_cndmask_b32_e32 v168, v168, v169, vcc
	v_rsq_f32_e32 v168, v168
	s_nop 0
	v_mul_f32_e32 v169, 0x45800000, v168
	v_cndmask_b32_e32 v168, v168, v169, vcc
	v_pk_mul_f32 v[64:65], v[64:65], v[168:169] op_sel_hi:[1,0]
	v_pk_mul_f32 v[66:67], v[66:67], v[168:169] op_sel_hi:[1,0]
	v_pk_mul_f32 v[64:65], v[0:1], v[64:65]
	v_pk_mul_f32 v[66:67], v[2:3], v[66:67]
	global_store_dwordx4 v128, v[64:67], s[0:1] nt
	s_nop 1
	v_pk_mul_f32 v[64:65], v[68:69], v[168:169] op_sel_hi:[1,0]
	v_pk_mul_f32 v[66:67], v[70:71], v[168:169] op_sel_hi:[1,0]
	v_pk_mul_f32 v[64:65], v[4:5], v[64:65]
	v_pk_mul_f32 v[66:67], v[6:7], v[66:67]
	global_store_dwordx4 v128, v[64:67], s[0:1] offset:1024 nt
	v_add_co_u32_e32 v68, vcc, s12, v170
	s_nop 0
	v_pk_mul_f32 v[64:65], v[72:73], v[168:169] op_sel_hi:[1,0]
	v_pk_mul_f32 v[66:67], v[74:75], v[168:169] op_sel_hi:[1,0]
	v_pk_mul_f32 v[64:65], v[8:9], v[64:65]
	v_pk_mul_f32 v[66:67], v[10:11], v[66:67]
	global_store_dwordx4 v128, v[64:67], s[0:1] offset:2048 nt
	v_addc_co_u32_e32 v69, vcc, 0, v171, vcc
	s_nop 0
	v_pk_mul_f32 v[64:65], v[76:77], v[168:169] op_sel_hi:[1,0]
	v_pk_mul_f32 v[66:67], v[78:79], v[168:169] op_sel_hi:[1,0]
	v_pk_mul_f32 v[64:65], v[12:13], v[64:65]
	v_pk_mul_f32 v[66:67], v[14:15], v[66:67]
	global_store_dwordx4 v128, v[64:67], s[0:1] offset:3072 nt
	v_add_co_u32_e32 v70, vcc, s14, v170
	s_nop 0
	v_pk_mul_f32 v[64:65], v[80:81], v[168:169] op_sel_hi:[1,0]
	v_pk_mul_f32 v[66:67], v[82:83], v[168:169] op_sel_hi:[1,0]
	v_pk_mul_f32 v[64:65], v[16:17], v[64:65]
	v_pk_mul_f32 v[66:67], v[18:19], v[66:67]
	v_addc_co_u32_e32 v71, vcc, 0, v171, vcc
	global_store_dwordx4 v[70:71], v[64:67], off offset:-4096 nt
	s_nop 1
	v_pk_mul_f32 v[64:65], v[84:85], v[168:169] op_sel_hi:[1,0]
	v_pk_mul_f32 v[66:67], v[86:87], v[168:169] op_sel_hi:[1,0]
	v_pk_mul_f32 v[64:65], v[20:21], v[64:65]
	v_pk_mul_f32 v[66:67], v[22:23], v[66:67]
	global_store_dwordx4 v[68:69], v[64:67], off offset:1024 nt
	s_nop 1
	v_pk_mul_f32 v[64:65], v[88:89], v[168:169] op_sel_hi:[1,0]
	v_pk_mul_f32 v[66:67], v[90:91], v[168:169] op_sel_hi:[1,0]
	v_pk_mul_f32 v[64:65], v[24:25], v[64:65]
	v_pk_mul_f32 v[66:67], v[26:27], v[66:67]
	global_store_dwordx4 v[68:69], v[64:67], off offset:2048 nt
	s_nop 1
	v_pk_mul_f32 v[64:65], v[92:93], v[168:169] op_sel_hi:[1,0]
	v_pk_mul_f32 v[66:67], v[94:95], v[168:169] op_sel_hi:[1,0]
	v_pk_mul_f32 v[64:65], v[28:29], v[64:65]
	v_pk_mul_f32 v[66:67], v[30:31], v[66:67]
	global_store_dwordx4 v[68:69], v[64:67], off offset:3072 nt
	v_add_co_u32_e32 v68, vcc, s15, v170
	s_nop 0
	v_pk_mul_f32 v[64:65], v[96:97], v[168:169] op_sel_hi:[1,0]
	v_pk_mul_f32 v[66:67], v[98:99], v[168:169] op_sel_hi:[1,0]
	v_pk_mul_f32 v[64:65], v[32:33], v[64:65]
	v_pk_mul_f32 v[66:67], v[34:35], v[66:67]
	global_store_dwordx4 v[70:71], v[64:67], off nt
	v_addc_co_u32_e32 v69, vcc, 0, v171, vcc
	s_nop 0
	v_pk_mul_f32 v[64:65], v[100:101], v[168:169] op_sel_hi:[1,0]
	v_pk_mul_f32 v[66:67], v[102:103], v[168:169] op_sel_hi:[1,0]
	v_pk_mul_f32 v[64:65], v[36:37], v[64:65]
	v_pk_mul_f32 v[66:67], v[38:39], v[66:67]
	global_store_dwordx4 v[70:71], v[64:67], off offset:1024 nt
	s_nop 1
	v_pk_mul_f32 v[64:65], v[104:105], v[168:169] op_sel_hi:[1,0]
	v_pk_mul_f32 v[66:67], v[106:107], v[168:169] op_sel_hi:[1,0]
	v_pk_mul_f32 v[64:65], v[40:41], v[64:65]
	v_pk_mul_f32 v[66:67], v[42:43], v[66:67]
	global_store_dwordx4 v[70:71], v[64:67], off offset:2048 nt
	s_nop 1
	v_pk_mul_f32 v[64:65], v[108:109], v[168:169] op_sel_hi:[1,0]
	v_pk_mul_f32 v[66:67], v[110:111], v[168:169] op_sel_hi:[1,0]
	v_pk_mul_f32 v[64:65], v[44:45], v[64:65]
	v_pk_mul_f32 v[66:67], v[46:47], v[66:67]
	global_store_dwordx4 v[70:71], v[64:67], off offset:3072 nt
	s_nop 1
	v_pk_mul_f32 v[64:65], v[112:113], v[168:169] op_sel_hi:[1,0]
	v_pk_mul_f32 v[66:67], v[114:115], v[168:169] op_sel_hi:[1,0]
	v_pk_mul_f32 v[64:65], v[48:49], v[64:65]
	v_pk_mul_f32 v[66:67], v[50:51], v[66:67]
	global_store_dwordx4 v[68:69], v[64:67], off nt
	s_nop 1
	v_pk_mul_f32 v[64:65], v[116:117], v[168:169] op_sel_hi:[1,0]
	v_pk_mul_f32 v[66:67], v[118:119], v[168:169] op_sel_hi:[1,0]
	v_pk_mul_f32 v[64:65], v[52:53], v[64:65]
	v_pk_mul_f32 v[66:67], v[54:55], v[66:67]
	global_store_dwordx4 v[68:69], v[64:67], off offset:1024 nt
	s_nop 1
	v_pk_mul_f32 v[64:65], v[120:121], v[168:169] op_sel_hi:[1,0]
	v_pk_mul_f32 v[66:67], v[122:123], v[168:169] op_sel_hi:[1,0]
	v_pk_mul_f32 v[64:65], v[56:57], v[64:65]
	v_pk_mul_f32 v[66:67], v[58:59], v[66:67]
	global_store_dwordx4 v[68:69], v[64:67], off offset:2048 nt
	s_nop 1
	v_pk_mul_f32 v[64:65], v[124:125], v[168:169] op_sel_hi:[1,0]
	v_pk_mul_f32 v[66:67], v[126:127], v[168:169] op_sel_hi:[1,0]
	v_pk_mul_f32 v[64:65], v[60:61], v[64:65]
	v_pk_mul_f32 v[66:67], v[62:63], v[66:67]
	global_store_dwordx4 v[68:69], v[64:67], off offset:3072 nt

; #define LAS __attribute__((address_space(3)))
; __device__ __forceinline__ float bf_lo(unsigned w) { return __uint_as_float(w << 16); }
; __device__ __forceinline__ float bf_hi(unsigned w) { return __uint_as_float(w & 0xffff0000u); }
; __device__ __forceinline__ f32x4 ld_bf4(const bf16_t* p) { const u32x2 w = *(const u32x2*)p; return (f32x4){bf_lo(w.x), bf_hi(w.x), bf_lo(w.y), bf_hi(w.y)}; }
; __device__ __forceinline__ void pf_row_finish(Frame& F, const LAS signed char* rem, int row, const u32x2 (&w)[16], const f32x4 (&gfv)[16]) {
;     const bf16_t* PART = WSP(bf16_t, WS_PART); const bf16_t* X1 = WSP(bf16_t, WS_X1);
;     float* o = F.out + (size_t)row * DM; f32x4 v[16]; float ss = 0.f;
; #pragma unroll
;     for (int j = 0; j < 16; ++j) { const int c = 256 * j + 4 * F.lane; const int tl = rem[(row >> 8) * 16 + j];
;         if (tl < 0) v[j] = (f32x4){bf_lo(w[j].x), bf_hi(w[j].x), bf_lo(w[j].y), bf_hi(w[j].y)};
;         else { f32x4 a = ld_bf4(X1 + (size_t)row * DM + c);
; #pragma unroll
;             for (int ks = 0; ks < 8; ++ks) a += ld_bf4(PART + ((size_t)(tl * 8 + ks) << 16) + (row & 255) * 256 + 4 * F.lane);
;             v[j] = a; }
;         ss += (v[j][0] * v[j][0] + v[j][1] * v[j][1]) + (v[j][2] * v[j][2] + v[j][3] * v[j][3]); }
;     const float rs = rsqrtf(wave_sum(ss) * (1.0f / DM) + EPS);
.LBB0_3021:
	v_pk_mul_f32 v[202:203], v[66:67], v[66:67]
	v_pk_mul_f32 v[206:207], v[64:65], v[64:65]
	v_mul_f32_e32 v173, v76, v76
	v_pk_mov_b32 v[208:209], v[206:207], v[202:203] op_sel:[1,0]
	v_mov_b32_e32 v207, v203
	v_pk_add_f32 v[202:203], v[208:209], v[206:207]
	v_pk_mul_f32 v[206:207], v[70:71], v[70:71]
	v_pk_mul_f32 v[208:209], v[68:69], v[68:69]
	v_pk_add_f32 v[202:203], v[202:203], v[202:203] op_sel:[0,1] op_sel_hi:[1,0]
	v_pk_mov_b32 v[210:211], v[208:209], v[206:207] op_sel:[1,0]
	v_mov_b32_e32 v209, v207
	v_pk_add_f32 v[206:207], v[210:211], v[208:209]
	v_mul_f32_e32 v208, v77, v77
	v_pk_add_f32 v[206:207], v[206:207], v[206:207] op_sel:[0,1] op_sel_hi:[1,0]
	v_mov_b32_e32 v203, v173
	v_mov_b32_e32 v207, v208
	v_pk_add_f32 v[202:203], v[202:203], v[206:207]
	v_mul_f32_e32 v206, v73, v73
	v_mul_f32_e32 v209, v78, v78
	v_pk_fma_f32 v[206:207], v[72:73], v[72:73], v[206:207] op_sel_hi:[1,1,0]
	v_mul_f32_e32 v208, v75, v75
	v_mul_f32_e32 v210, v79, v79
	v_mov_b32_e32 v207, v209
	v_pk_fma_f32 v[208:209], v[74:75], v[74:75], v[208:209] op_sel_hi:[1,1,0]
	v_mul_f32_e32 v173, v88, v88
	v_mov_b32_e32 v209, v210
	v_pk_add_f32 v[206:207], v[206:207], v[208:209]
	v_pk_mul_f32 v[208:209], v[80:81], v[80:81]
	v_pk_add_f32 v[202:203], v[202:203], v[206:207]
	v_pk_mul_f32 v[206:207], v[82:83], v[82:83]
	v_pk_add_f32 v[202:203], v[202:203], v[202:203] op_sel:[0,1] op_sel_hi:[1,0]
	v_pk_mov_b32 v[210:211], v[208:209], v[206:207] op_sel:[1,0]
	v_mov_b32_e32 v209, v207
	v_pk_add_f32 v[206:207], v[210:211], v[208:209]
	v_mul_f32_e32 v208, v89, v89
	v_pk_add_f32 v[206:207], v[206:207], v[206:207] op_sel:[0,1] op_sel_hi:[1,0]
	v_mov_b32_e32 v203, v173
	v_mov_b32_e32 v207, v208
	v_pk_add_f32 v[202:203], v[202:203], v[206:207]
	v_mul_f32_e32 v206, v85, v85
	v_mul_f32_e32 v209, v90, v90
	v_pk_fma_f32 v[206:207], v[84:85], v[84:85], v[206:207] op_sel_hi:[1,1,0]
	v_mul_f32_e32 v208, v87, v87
	v_mul_f32_e32 v210, v91, v91
	v_mov_b32_e32 v207, v209
	v_pk_fma_f32 v[208:209], v[86:87], v[86:87], v[208:209] op_sel_hi:[1,1,0]
	v_mul_f32_e32 v173, v100, v100
	v_mov_b32_e32 v209, v210
	v_pk_add_f32 v[206:207], v[206:207], v[208:209]
	v_pk_mul_f32 v[208:209], v[92:93], v[92:93]
	v_pk_add_f32 v[202:203], v[202:203], v[206:207]
	v_pk_mul_f32 v[206:207], v[94:95], v[94:95]
	v_pk_add_f32 v[202:203], v[202:203], v[202:203] op_sel:[0,1] op_sel_hi:[1,0]
	v_pk_mov_b32 v[210:211], v[208:209], v[206:207] op_sel:[1,0]
	v_mov_b32_e32 v209, v207
	v_pk_add_f32 v[206:207], v[210:211], v[208:209]
	v_mul_f32_e32 v208, v101, v101
	v_pk_add_f32 v[206:207], v[206:207], v[206:207] op_sel:[0,1] op_sel_hi:[1,0]
	v_mov_b32_e32 v203, v173
	v_mov_b32_e32 v207, v208
	v_pk_add_f32 v[202:203], v[202:203], v[206:207]
	v_mul_f32_e32 v206, v97, v97
	v_mul_f32_e32 v209, v102, v102
	v_pk_fma_f32 v[206:207], v[96:97], v[96:97], v[206:207] op_sel_hi:[1,1,0]
	v_mul_f32_e32 v208, v99, v99
	v_mul_f32_e32 v210, v103, v103
	v_mov_b32_e32 v207, v209
	v_pk_fma_f32 v[208:209], v[98:99], v[98:99], v[208:209] op_sel_hi:[1,1,0]
	v_mul_f32_e32 v173, v112, v112
	v_mov_b32_e32 v209, v210
	v_pk_add_f32 v[206:207], v[206:207], v[208:209]
	v_pk_mul_f32 v[208:209], v[104:105], v[104:105]
	v_pk_add_f32 v[202:203], v[202:203], v[206:207]
	v_pk_mul_f32 v[206:207], v[106:107], v[106:107]
	v_pk_add_f32 v[202:203], v[202:203], v[202:203] op_sel:[0,1] op_sel_hi:[1,0]
	v_pk_mov_b32 v[210:211], v[208:209], v[206:207] op_sel:[1,0]
	v_mov_b32_e32 v209, v207
	v_pk_add_f32 v[206:207], v[210:211], v[208:209]
	v_mul_f32_e32 v208, v113, v113
	v_pk_add_f32 v[206:207], v[206:207], v[206:207] op_sel:[0,1] op_sel_hi:[1,0]
	v_mov_b32_e32 v203, v173
	v_mov_b32_e32 v207, v208
	v_pk_add_f32 v[202:203], v[202:203], v[206:207]
	v_mul_f32_e32 v206, v109, v109
	v_mul_f32_e32 v209, v114, v114
	v_pk_fma_f32 v[206:207], v[108:109], v[108:109], v[206:207] op_sel_hi:[1,1,0]
	v_mul_f32_e32 v208, v111, v111
	v_mul_f32_e32 v210, v115, v115
	v_mov_b32_e32 v207, v209
	v_pk_fma_f32 v[208:209], v[110:111], v[110:111], v[208:209] op_sel_hi:[1,1,0]
	v_mul_f32_e32 v173, v124, v124
	v_mov_b32_e32 v209, v210
	v_pk_add_f32 v[206:207], v[206:207], v[208:209]
	v_pk_mul_f32 v[208:209], v[116:117], v[116:117]
	v_pk_add_f32 v[202:203], v[202:203], v[206:207]
	v_pk_mul_f32 v[206:207], v[118:119], v[118:119]
	v_pk_add_f32 v[202:203], v[202:203], v[202:203] op_sel:[0,1] op_sel_hi:[1,0]
	v_pk_mov_b32 v[210:211], v[208:209], v[206:207] op_sel:[1,0]
	v_mov_b32_e32 v209, v207
	v_pk_add_f32 v[206:207], v[210:211], v[208:209]
	v_mul_f32_e32 v208, v125, v125
	v_pk_add_f32 v[206:207], v[206:207], v[206:207] op_sel:[0,1] op_sel_hi:[1,0]
	v_mov_b32_e32 v203, v173
	v_mov_b32_e32 v207, v208
	v_pk_add_f32 v[202:203], v[202:203], v[206:207]
	v_mul_f32_e32 v206, v121, v121
	v_mul_f32_e32 v209, v126, v126
	v_pk_fma_f32 v[206:207], v[120:121], v[120:121], v[206:207] op_sel_hi:[1,1,0]
	v_mul_f32_e32 v208, v123, v123
	v_mul_f32_e32 v210, v127, v127
	v_mov_b32_e32 v207, v209
	v_pk_fma_f32 v[208:209], v[122:123], v[122:123], v[208:209] op_sel_hi:[1,1,0]
	s_lshl_b64 s[0:1], s[0:1], 2
	v_mov_b32_e32 v209, v210
	v_pk_add_f32 v[206:207], v[206:207], v[208:209]
	s_add_u32 s0, s84, s0
	v_pk_add_f32 v[202:203], v[202:203], v[206:207]
	s_addc_u32 s1, s85, s1
	v_add_f32_e32 v173, v202, v203
	v_and_b32_e32 v202, 64, v205
	v_add_u32_e32 v202, 64, v202
	v_xor_b32_e32 v203, 1, v205
	v_cmp_lt_i32_e32 vcc, v203, v202
	v_lshl_add_u64 v[212:213], s[0:1], 0, v[128:129]
	s_nop 0
	v_cndmask_b32_e32 v203, v205, v203, vcc
	v_lshlrev_b32_e32 v206, 2, v203
	ds_bpermute_b32 v203, v206, v173
	s_waitcnt lgkmcnt(0)
; #define LAS __attribute__((address_space(3)))
; __device__ __forceinline__ float bf_lo(unsigned w) { return __uint_as_float(w << 16); }
; __device__ __forceinline__ float bf_hi(unsigned w) { return __uint_as_float(w & 0xffff0000u); }
; __device__ __forceinline__ f32x4 ld_bf4(const bf16_t* p) { const u32x2 w = *(const u32x2*)p; return (f32x4){bf_lo(w.x), bf_hi(w.x), bf_lo(w.y), bf_hi(w.y)}; }
; __device__ __forceinline__ void pf_row_finish(Frame& F, const LAS signed char* rem, int row, const u32x2 (&w)[16], const f32x4 (&gfv)[16]) {
;     const bf16_t* PART = WSP(bf16_t, WS_PART); const bf16_t* X1 = WSP(bf16_t, WS_X1);
;     float* o = F.out + (size_t)row * DM; f32x4 v[16]; float ss = 0.f;
; #pragma unroll
;     for (int j = 0; j < 16; ++j) { const int c = 256 * j + 4 * F.lane; const int tl = rem[(row >> 8) * 16 + j];
;         if (tl < 0) v[j] = (f32x4){bf_lo(w[j].x), bf_hi(w[j].x), bf_lo(w[j].y), bf_hi(w[j].y)};
;         else { f32x4 a = ld_bf4(X1 + (size_t)row * DM + c);
; #pragma unroll
;             for (int ks = 0; ks < 8; ++ks) a += ld_bf4(PART + ((size_t)(tl * 8 + ks) << 16) + (row & 255) * 256 + 4 * F.lane);
;             v[j] = a; }
;         ss += (v[j][0] * v[j][0] + v[j][1] * v[j][1]) + (v[j][2] * v[j][2] + v[j][3] * v[j][3]); }
;     const float rs = rsqrtf(wave_sum(ss) * (1.0f / DM) + EPS);
; #pragma unroll
;     for (int j = 0; j < 16; ++j) *(f32x4*)(o + 256 * j + 4 * F.lane) = v[j] * rs * gfv[j];
; }
	v_add_f32_e32 v173, v173, v203
	v_xor_b32_e32 v203, 2, v205
	v_cmp_lt_i32_e32 vcc, v203, v202
	s_nop 1
	v_cndmask_b32_e32 v203, v205, v203, vcc
	v_lshlrev_b32_e32 v207, 2, v203
	ds_bpermute_b32 v203, v207, v173
	s_waitcnt lgkmcnt(0)
	v_add_f32_e32 v173, v173, v203
	v_xor_b32_e32 v203, 4, v205
	v_cmp_lt_i32_e32 vcc, v203, v202
	s_nop 1
	v_cndmask_b32_e32 v203, v205, v203, vcc
	v_lshlrev_b32_e32 v208, 2, v203
	ds_bpermute_b32 v203, v208, v173
	s_waitcnt lgkmcnt(0)
	v_add_f32_e32 v173, v173, v203
	v_xor_b32_e32 v203, 8, v205
	v_cmp_lt_i32_e32 vcc, v203, v202
	s_nop 1
	v_cndmask_b32_e32 v203, v205, v203, vcc
	v_lshlrev_b32_e32 v209, 2, v203
	ds_bpermute_b32 v203, v209, v173
	s_waitcnt lgkmcnt(0)
	v_add_f32_e32 v173, v173, v203
	v_xor_b32_e32 v203, 16, v205
	v_cmp_lt_i32_e32 vcc, v203, v202
	s_nop 1
	v_cndmask_b32_e32 v203, v205, v203, vcc
	v_lshlrev_b32_e32 v210, 2, v203
	ds_bpermute_b32 v203, v210, v173
	s_waitcnt lgkmcnt(0)
	v_add_f32_e32 v173, v173, v203
	v_xor_b32_e32 v203, 32, v205
	v_cmp_lt_i32_e32 vcc, v203, v202
	s_nop 1
	v_cndmask_b32_e32 v202, v205, v203, vcc
	v_lshlrev_b32_e32 v211, 2, v202
	ds_bpermute_b32 v202, v211, v173
	s_waitcnt lgkmcnt(0)
	v_add_f32_e32 v173, v173, v202
	v_fmamk_f32 v173, v173, 0x39800000, v145
	v_mul_f32_e32 v202, 0x4b800000, v173
	v_cmp_gt_f32_e32 vcc, s30, v173
	s_nop 1
	v_cndmask_b32_e32 v173, v173, v202, vcc
	v_rsq_f32_e32 v173, v173
	s_nop 0
	v_mul_f32_e32 v202, 0x45800000, v173
	v_cndmask_b32_e32 v202, v173, v202, vcc
	v_pk_mul_f32 v[64:65], v[64:65], v[202:203] op_sel_hi:[1,0]
	v_pk_mul_f32 v[66:67], v[66:67], v[202:203] op_sel_hi:[1,0]
	s_waitcnt vmcnt(47)
	v_pk_mul_f32 v[64:65], v[0:1], v[64:65]
	v_pk_mul_f32 v[66:67], v[2:3], v[66:67]
	global_store_dwordx4 v128, v[64:67], s[0:1] nt
	s_nop 1
	v_pk_mul_f32 v[64:65], v[68:69], v[202:203] op_sel_hi:[1,0]
	v_pk_mul_f32 v[66:67], v[70:71], v[202:203] op_sel_hi:[1,0]
	s_waitcnt vmcnt(47)
	v_pk_mul_f32 v[64:65], v[4:5], v[64:65]
	v_pk_mul_f32 v[66:67], v[6:7], v[66:67]
	global_store_dwordx4 v128, v[64:67], s[0:1] offset:1024 nt
	v_add_co_u32_e32 v68, vcc, s12, v212
	s_nop 0
	v_pk_mul_f32 v[64:65], v[72:73], v[202:203] op_sel_hi:[1,0]
	v_pk_mul_f32 v[66:67], v[74:75], v[202:203] op_sel_hi:[1,0]
	s_waitcnt vmcnt(47)
	v_pk_mul_f32 v[64:65], v[8:9], v[64:65]
	v_pk_mul_f32 v[66:67], v[10:11], v[66:67]
	global_store_dwordx4 v128, v[64:67], s[0:1] offset:2048 nt
	v_addc_co_u32_e32 v69, vcc, 0, v213, vcc
	s_nop 0
	v_pk_mul_f32 v[64:65], v[76:77], v[202:203] op_sel_hi:[1,0]
	v_pk_mul_f32 v[66:67], v[78:79], v[202:203] op_sel_hi:[1,0]
	s_waitcnt vmcnt(47)
	v_pk_mul_f32 v[64:65], v[12:13], v[64:65]
	v_pk_mul_f32 v[66:67], v[14:15], v[66:67]
	global_store_dwordx4 v128, v[64:67], s[0:1] offset:3072 nt
	v_add_co_u32_e32 v70, vcc, s14, v212
	s_nop 0
	v_pk_mul_f32 v[64:65], v[80:81], v[202:203] op_sel_hi:[1,0]
	v_pk_mul_f32 v[66:67], v[82:83], v[202:203] op_sel_hi:[1,0]
	s_waitcnt vmcnt(47)
	v_pk_mul_f32 v[64:65], v[16:17], v[64:65]
	v_pk_mul_f32 v[66:67], v[18:19], v[66:67]
	v_addc_co_u32_e32 v71, vcc, 0, v213, vcc
	global_store_dwordx4 v[70:71], v[64:67], off offset:-4096 nt
	s_nop 1
	v_pk_mul_f32 v[64:65], v[84:85], v[202:203] op_sel_hi:[1,0]
	v_pk_mul_f32 v[66:67], v[86:87], v[202:203] op_sel_hi:[1,0]
	s_waitcnt vmcnt(47)
	v_pk_mul_f32 v[64:65], v[20:21], v[64:65]
	v_pk_mul_f32 v[66:67], v[22:23], v[66:67]
	global_store_dwordx4 v[68:69], v[64:67], off offset:1024 nt
	s_nop 1
	v_pk_mul_f32 v[64:65], v[88:89], v[202:203] op_sel_hi:[1,0]
	v_pk_mul_f32 v[66:67], v[90:91], v[202:203] op_sel_hi:[1,0]
	s_waitcnt vmcnt(47)
	v_pk_mul_f32 v[64:65], v[24:25], v[64:65]
	v_pk_mul_f32 v[66:67], v[26:27], v[66:67]
	global_store_dwordx4 v[68:69], v[64:67], off offset:2048 nt
	s_nop 1
	v_pk_mul_f32 v[64:65], v[92:93], v[202:203] op_sel_hi:[1,0]
	v_pk_mul_f32 v[66:67], v[94:95], v[202:203] op_sel_hi:[1,0]
	s_waitcnt vmcnt(47)
	v_pk_mul_f32 v[64:65], v[28:29], v[64:65]
	v_pk_mul_f32 v[66:67], v[30:31], v[66:67]
	global_store_dwordx4 v[68:69], v[64:67], off offset:3072 nt
	v_add_co_u32_e32 v68, vcc, s15, v212
	s_nop 0
	v_pk_mul_f32 v[64:65], v[96:97], v[202:203] op_sel_hi:[1,0]
	v_pk_mul_f32 v[66:67], v[98:99], v[202:203] op_sel_hi:[1,0]
	s_waitcnt vmcnt(47)
	v_pk_mul_f32 v[64:65], v[32:33], v[64:65]
	v_pk_mul_f32 v[66:67], v[34:35], v[66:67]
	global_store_dwordx4 v[70:71], v[64:67], off nt
	v_addc_co_u32_e32 v69, vcc, 0, v213, vcc
	s_nop 0
	v_pk_mul_f32 v[64:65], v[100:101], v[202:203] op_sel_hi:[1,0]
	v_pk_mul_f32 v[66:67], v[102:103], v[202:203] op_sel_hi:[1,0]
	s_waitcnt vmcnt(47)
	v_pk_mul_f32 v[64:65], v[36:37], v[64:65]
	v_pk_mul_f32 v[66:67], v[38:39], v[66:67]
	global_store_dwordx4 v[70:71], v[64:67], off offset:1024 nt
	s_nop 1
	v_pk_mul_f32 v[64:65], v[104:105], v[202:203] op_sel_hi:[1,0]
	v_pk_mul_f32 v[66:67], v[106:107], v[202:203] op_sel_hi:[1,0]
	s_waitcnt vmcnt(47)
	v_pk_mul_f32 v[64:65], v[40:41], v[64:65]
	v_pk_mul_f32 v[66:67], v[42:43], v[66:67]
	global_store_dwordx4 v[70:71], v[64:67], off offset:2048 nt
	s_nop 1
	v_pk_mul_f32 v[64:65], v[108:109], v[202:203] op_sel_hi:[1,0]
	v_pk_mul_f32 v[66:67], v[110:111], v[202:203] op_sel_hi:[1,0]
	s_waitcnt vmcnt(47)
	v_pk_mul_f32 v[64:65], v[44:45], v[64:65]
	v_pk_mul_f32 v[66:67], v[46:47], v[66:67]
	global_store_dwordx4 v[70:71], v[64:67], off offset:3072 nt
	s_nop 1
	v_pk_mul_f32 v[64:65], v[112:113], v[202:203] op_sel_hi:[1,0]
	v_pk_mul_f32 v[66:67], v[114:115], v[202:203] op_sel_hi:[1,0]
	s_waitcnt vmcnt(47)
	v_pk_mul_f32 v[64:65], v[48:49], v[64:65]
	v_pk_mul_f32 v[66:67], v[50:51], v[66:67]
	global_store_dwordx4 v[68:69], v[64:67], off nt
	s_nop 1
	v_pk_mul_f32 v[64:65], v[116:117], v[202:203] op_sel_hi:[1,0]
	v_pk_mul_f32 v[66:67], v[118:119], v[202:203] op_sel_hi:[1,0]
	s_waitcnt vmcnt(47)
	v_pk_mul_f32 v[64:65], v[52:53], v[64:65]
	v_pk_mul_f32 v[66:67], v[54:55], v[66:67]
	global_store_dwordx4 v[68:69], v[64:67], off offset:1024 nt
	s_nop 1
	v_pk_mul_f32 v[64:65], v[120:121], v[202:203] op_sel_hi:[1,0]
	v_pk_mul_f32 v[66:67], v[122:123], v[202:203] op_sel_hi:[1,0]
	s_waitcnt vmcnt(47)
	v_pk_mul_f32 v[64:65], v[56:57], v[64:65]
	v_pk_mul_f32 v[66:67], v[58:59], v[66:67]
	global_store_dwordx4 v[68:69], v[64:67], off offset:2048 nt
	s_nop 1
	v_pk_mul_f32 v[64:65], v[124:125], v[202:203] op_sel_hi:[1,0]
	v_pk_mul_f32 v[66:67], v[126:127], v[202:203] op_sel_hi:[1,0]
	s_waitcnt vmcnt(47)
	v_pk_mul_f32 v[64:65], v[60:61], v[64:65]
	v_pk_mul_f32 v[66:67], v[62:63], v[66:67]
	global_store_dwordx4 v[68:69], v[64:67], off offset:3072 nt
	s_cmp_gt_i32 s31, s13
	s_cbranch_scc1 .LBB0_2956
; __device__ __forceinline__ float bf_lo(unsigned w) { return __uint_as_float(w << 16); }
; __device__ __forceinline__ float bf_hi(unsigned w) { return __uint_as_float(w & 0xffff0000u); }
; __device__ __forceinline__ f32x4 ld_bf4(const bf16_t* p) { const u32x2 w = *(const u32x2*)p; return (f32x4){bf_lo(w.x), bf_hi(w.x), bf_lo(w.y), bf_hi(w.y)}; }
; __device__ __forceinline__ void p7_row_load(const bf16_t* X1, int row, int lane, u32x2 (&w)[16]) {
; #pragma unroll
;     for (int j = 0; j < 16; ++j) w[j] = *(const u32x2*)(X1 + (size_t)row * DM + 256 * j + 4 * lane);
; }
; __device__ __forceinline__ void pf_row_finish(Frame& F, const LAS signed char* rem, int row, const u32x2 (&w)[16], const f32x4 (&gfv)[16]) {
;     ...
; #pragma unroll
;     for (int j = 0; j < 16; ++j) { const int c = 256 * j + 4 * F.lane; const int tl = rem[(row >> 8) * 16 + j];
;         if (tl < 0) v[j] = (f32x4){bf_lo(w[j].x), bf_hi(w[j].x), bf_lo(w[j].y), bf_hi(w[j].y)};
;         else { f32x4 a = ld_bf4(X1 + (size_t)row * DM + c);
; #pragma unroll
;             for (int ks = 0; ks < 8; ++ks) a += ld_bf4(PART + ((size_t)(tl * 8 + ks) << 16) + (row & 255) * 256 + 4 * F.lane);
;             v[j] = a; }
	s_add_i32 s0, s21, s92
	s_min_i32 s0, s0, s13
	s_ashr_i32 s1, s0, 31
	s_lshl_b64 s[0:1], s[0:1], 13
	v_lshl_add_u64 v[64:65], v[148:149], 0, s[0:1]
	global_load_dwordx2 v[130:131], v[64:65], off
	global_load_dwordx2 v[132:133], v[64:65], off offset:512
	global_load_dwordx2 v[134:135], v[64:65], off offset:1024
	global_load_dwordx2 v[136:137], v[64:65], off offset:1536
	global_load_dwordx2 v[138:139], v[64:65], off offset:2048
	global_load_dwordx2 v[140:141], v[64:65], off offset:2560
	global_load_dwordx2 v[142:143], v[64:65], off offset:3072
	global_load_dwordx2 v[146:147], v[64:65], off offset:3584
	v_add_co_u32_e32 v64, vcc, 0x1000, v64
	s_nop 1
	v_addc_co_u32_e32 v65, vcc, 0, v65, vcc
	global_load_dwordx2 v[152:153], v[64:65], off
	global_load_dwordx2 v[154:155], v[64:65], off offset:512
	global_load_dwordx2 v[156:157], v[64:65], off offset:1024
	global_load_dwordx2 v[158:159], v[64:65], off offset:1536
	global_load_dwordx2 v[160:161], v[64:65], off offset:2048
	global_load_dwordx2 v[162:163], v[64:65], off offset:2560
	global_load_dwordx2 v[164:165], v[64:65], off offset:3072
	global_load_dwordx2 v[166:167], v[64:65], off offset:3584
	s_ashr_i32 s0, s4, 4
	s_and_b32 s0, s0, -16
	s_add_i32 s8, s0, 0
	v_mov_b32_e32 v64, s8
	ds_read_i8 v68, v64
	s_add_u32 s6, s16, s6
	s_addc_u32 s7, s17, s7
	s_lshl_b32 s0, s4, 9
	s_and_b32 s2, s0, 0x1fe00
	s_waitcnt lgkmcnt(0)
	v_cmp_gt_i32_sdwa s[0:1], sext(v68), v204 src0_sel:WORD_0 src1_sel:DWORD
	v_lshl_add_u64 v[202:203], v[150:151], 0, s[2:3]
	s_and_b64 vcc, exec, s[0:1]
	s_mov_b64 s[0:1], -1
	s_cbranch_vccz .LBB0_3024
	v_lshlrev_b32_e32 v66, 20, v68
	v_mov_b32_e32 v67, v129
	v_lshl_add_u64 v[66:67], v[202:203], 0, v[66:67]
	v_add_co_u32_e32 v68, vcc, s23, v66
	global_load_dwordx2 v[64:65], v172, s[6:7]
	s_nop 0
	v_addc_co_u32_e32 v69, vcc, 0, v67, vcc
	v_add_co_u32_e32 v72, vcc, s24, v66
	global_load_dwordx2 v[70:71], v[66:67], off
	s_nop 0
	global_load_dwordx2 v[68:69], v[68:69], off
	v_addc_co_u32_e32 v73, vcc, 0, v67, vcc
	v_add_co_u32_e32 v74, vcc, s25, v66
	s_mov_b64 s[0:1], 0
	s_nop 0
	v_addc_co_u32_e32 v75, vcc, 0, v67, vcc
	v_add_co_u32_e32 v76, vcc, s26, v66
	global_load_dwordx2 v[72:73], v[72:73], off
	s_nop 0
	global_load_dwordx2 v[74:75], v[74:75], off
	v_addc_co_u32_e32 v77, vcc, 0, v67, vcc
	v_add_co_u32_e32 v78, vcc, s27, v66
	global_load_dwordx2 v[76:77], v[76:77], off
	s_nop 0
	v_addc_co_u32_e32 v79, vcc, 0, v67, vcc
	v_add_co_u32_e32 v80, vcc, s28, v66
	global_load_dwordx2 v[78:79], v[78:79], off
	s_nop 0
	v_addc_co_u32_e32 v81, vcc, 0, v67, vcc
	v_add_co_u32_e32 v66, vcc, s29, v66
	global_load_dwordx2 v[80:81], v[80:81], off
	s_nop 0
	v_addc_co_u32_e32 v67, vcc, 0, v67, vcc
	global_load_dwordx2 v[66:67], v[66:67], off
	s_waitcnt vmcnt(8)
	v_lshlrev_b32_e32 v82, 16, v64
	v_and_b32_e32 v83, 0xffff0000, v64
	v_lshlrev_b32_e32 v64, 16, v65
	v_and_b32_e32 v65, 0xffff0000, v65
	s_waitcnt vmcnt(7)
	v_lshlrev_b32_e32 v84, 16, v70
	v_and_b32_e32 v85, 0xffff0000, v70
	v_lshlrev_b32_e32 v70, 16, v71
	v_and_b32_e32 v71, 0xffff0000, v71
	v_pk_add_f32 v[82:83], v[82:83], v[84:85]
	v_pk_add_f32 v[64:65], v[64:65], v[70:71]
	s_waitcnt vmcnt(6)
	v_lshlrev_b32_e32 v70, 16, v68
	v_and_b32_e32 v71, 0xffff0000, v68
	v_lshlrev_b32_e32 v68, 16, v69
	v_and_b32_e32 v69, 0xffff0000, v69
	s_waitcnt vmcnt(5)
	v_lshlrev_b32_e32 v84, 16, v72
	v_and_b32_e32 v85, 0xffff0000, v72
	v_lshlrev_b32_e32 v72, 16, v73
	v_and_b32_e32 v73, 0xffff0000, v73
	v_pk_add_f32 v[64:65], v[64:65], v[68:69]
	v_pk_add_f32 v[68:69], v[82:83], v[70:71]
	s_waitcnt vmcnt(4)
	v_lshlrev_b32_e32 v86, 16, v74
	v_and_b32_e32 v87, 0xffff0000, v74
	v_lshlrev_b32_e32 v74, 16, v75
	v_and_b32_e32 v75, 0xffff0000, v75
	v_pk_add_f32 v[68:69], v[68:69], v[84:85]
	v_pk_add_f32 v[64:65], v[64:65], v[72:73]
	s_waitcnt vmcnt(3)
	v_lshlrev_b32_e32 v88, 16, v76
	v_and_b32_e32 v89, 0xffff0000, v76
	v_lshlrev_b32_e32 v76, 16, v77
	v_and_b32_e32 v77, 0xffff0000, v77
	v_pk_add_f32 v[64:65], v[64:65], v[74:75]
	v_pk_add_f32 v[68:69], v[68:69], v[86:87]
	s_waitcnt vmcnt(2)
	v_lshlrev_b32_e32 v90, 16, v78
	v_and_b32_e32 v91, 0xffff0000, v78
	v_lshlrev_b32_e32 v78, 16, v79
	v_and_b32_e32 v79, 0xffff0000, v79
	v_pk_add_f32 v[68:69], v[68:69], v[88:89]
	v_pk_add_f32 v[64:65], v[64:65], v[76:77]
	s_waitcnt vmcnt(1)
	v_lshlrev_b32_e32 v92, 16, v80
	v_and_b32_e32 v93, 0xffff0000, v80
	v_lshlrev_b32_e32 v80, 16, v81
	v_and_b32_e32 v81, 0xffff0000, v81
	v_pk_add_f32 v[64:65], v[64:65], v[78:79]
	v_pk_add_f32 v[68:69], v[68:69], v[90:91]
	s_waitcnt vmcnt(0)
	v_lshlrev_b32_e32 v70, 16, v66
	v_and_b32_e32 v71, 0xffff0000, v66
	v_lshlrev_b32_e32 v66, 16, v67
	v_pk_add_f32 v[68:69], v[68:69], v[92:93]
	v_pk_add_f32 v[64:65], v[64:65], v[80:81]
	v_and_b32_e32 v67, 0xffff0000, v67
	v_pk_add_f32 v[66:67], v[64:65], v[66:67]
	v_pk_add_f32 v[64:65], v[68:69], v[70:71]
